# v60 + attention unit epilogue de-serialised: LDS combine of the two maps in batches of 7 reads in flight (counted lgkmcnt), the 16 sub-norm gain loads issued together with counted vmcnt
# speedup vs baseline: 1.0012x; 1.0003x over previous
; __device__ __forceinline__ void attn_unit(const bf16* __restrict__ qkvb, int seq, int q0, int h, ldsp_t ldsb, float* wsc, const float* tab, float lam) {
;     ...
;   asm volatile("s_waitcnt lgkmcnt(0)" ::: "memory"); __builtin_amdgcn_s_barrier(); asm volatile("" ::: "memory");
;   if (!mapw) {
; #pragma unroll
;     for (int r = 0; r < 16; ++r)
; #pragma unroll
;       for (int d = 0; d < 8; ++d) { const ldsf_t p_ = df + (((r & 3) + 8 * (r >> 2)) * 256 + ((d * 32 + r32) ^ ((d >> 1) << 2) ^ ((r & 3) << 4))); *p_ = *p_ + o[d][r] * rli[r]; }
;   }
.LBB0_586:
	s_waitcnt lgkmcnt(0)
	s_barrier
	s_andn2_b64 vcc, exec, s[4:5]
	s_cbranch_vccnz .LBB0_588
	ds_read2_b32 v[162:163], v159 offset0:0 offset1:32
	ds_read2_b32 v[164:165], v138 offset0:64 offset1:96
	ds_read2_b32 v[166:167], v137 offset0:128 offset1:160
	ds_read2_b32 v[168:169], v136 offset0:192 offset1:224
	v_add_u32_e32 v180, 0x400, v135
	ds_read2_b32 v[170:171], v180 offset0:0 offset1:32
	v_add_u32_e32 v181, 0x400, v133
	ds_read2_b32 v[172:173], v181 offset0:64 offset1:96
	v_add_u32_e32 v182, 0x400, v132
	ds_read2_b32 v[174:175], v182 offset0:128 offset1:160
	s_waitcnt lgkmcnt(6)
	v_fmac_f32_e32 v162, v98, v158
	v_fmac_f32_e32 v163, v114, v158
	ds_write2_b32 v159, v162, v163 offset0:0 offset1:32
	s_waitcnt lgkmcnt(6)
	v_fmac_f32_e32 v164, v66, v158
	v_fmac_f32_e32 v165, v82, v158
	ds_write2_b32 v138, v164, v165 offset0:64 offset1:96
	s_waitcnt lgkmcnt(6)
	v_fmac_f32_e32 v166, v34, v158
	v_fmac_f32_e32 v167, v50, v158
	ds_write2_b32 v137, v166, v167 offset0:128 offset1:160
	s_waitcnt lgkmcnt(6)
	v_fmac_f32_e32 v168, v18, v158
	v_fmac_f32_e32 v169, v2, v158
	ds_write2_b32 v136, v168, v169 offset0:192 offset1:224
	s_waitcnt lgkmcnt(6)
	v_fmac_f32_e32 v170, v99, v156
	v_fmac_f32_e32 v171, v115, v156
	ds_write2_b32 v180, v170, v171 offset0:0 offset1:32
	s_waitcnt lgkmcnt(6)
	v_fmac_f32_e32 v172, v67, v156
	v_fmac_f32_e32 v173, v83, v156
	ds_write2_b32 v181, v172, v173 offset0:64 offset1:96
	s_waitcnt lgkmcnt(6)
	v_fmac_f32_e32 v174, v35, v156
	v_fmac_f32_e32 v175, v51, v156
	ds_write2_b32 v182, v174, v175 offset0:128 offset1:160
	v_add_u32_e32 v176, 0x400, v131
	ds_read2_b32 v[162:163], v176 offset0:192 offset1:224
	ds_read2_b32 v[164:165], v157 offset0:0 offset1:32
	v_add_u32_e32 v178, 0x800, v138
	ds_read2_b32 v[166:167], v178 offset0:64 offset1:96
	v_add_u32_e32 v179, 0x800, v137
	ds_read2_b32 v[168:169], v179 offset0:128 offset1:160
	v_add_u32_e32 v180, 0x800, v136
	ds_read2_b32 v[170:171], v180 offset0:192 offset1:224
	v_add_u32_e32 v181, 0xc00, v135
	ds_read2_b32 v[172:173], v181 offset0:0 offset1:32
	v_add_u32_e32 v182, 0xc00, v133
	ds_read2_b32 v[174:175], v182 offset0:64 offset1:96
	s_waitcnt lgkmcnt(6)
	v_fmac_f32_e32 v162, v19, v156
	v_fmac_f32_e32 v163, v3, v156
	ds_write2_b32 v176, v162, v163 offset0:192 offset1:224
	s_waitcnt lgkmcnt(6)
	v_fmac_f32_e32 v164, v116, v155
	v_fmac_f32_e32 v165, v100, v155
	ds_write2_b32 v157, v164, v165 offset0:0 offset1:32
	s_waitcnt lgkmcnt(6)
	v_fmac_f32_e32 v166, v84, v155
	v_fmac_f32_e32 v167, v68, v155
	ds_write2_b32 v178, v166, v167 offset0:64 offset1:96
	s_waitcnt lgkmcnt(6)
	v_fmac_f32_e32 v168, v52, v155
	v_fmac_f32_e32 v169, v36, v155
	ds_write2_b32 v179, v168, v169 offset0:128 offset1:160
	s_waitcnt lgkmcnt(6)
	v_fmac_f32_e32 v170, v4, v155
	v_fmac_f32_e32 v171, v20, v155
	ds_write2_b32 v180, v170, v171 offset0:192 offset1:224
	s_waitcnt lgkmcnt(6)
	v_fmac_f32_e32 v172, v117, v153
	v_fmac_f32_e32 v173, v101, v153
	ds_write2_b32 v181, v172, v173 offset0:0 offset1:32
	s_waitcnt lgkmcnt(6)
	v_fmac_f32_e32 v174, v85, v153
	v_fmac_f32_e32 v175, v69, v153
	ds_write2_b32 v182, v174, v175 offset0:64 offset1:96
	v_add_u32_e32 v176, 0xc00, v132
	ds_read2_b32 v[162:163], v176 offset0:128 offset1:160
	v_add_u32_e32 v177, 0xc00, v131
	ds_read2_b32 v[164:165], v177 offset0:192 offset1:224
	ds_read2_b32 v[166:167], v154 offset0:0 offset1:32
	v_add_u32_e32 v179, 0x2000, v138
	ds_read2_b32 v[168:169], v179 offset0:64 offset1:96
	v_add_u32_e32 v180, 0x2000, v137
	ds_read2_b32 v[170:171], v180 offset0:128 offset1:160
	v_add_u32_e32 v181, 0x2000, v136
	ds_read2_b32 v[172:173], v181 offset0:192 offset1:224
	v_add_u32_e32 v182, 0x2400, v135
	ds_read2_b32 v[174:175], v182 offset0:0 offset1:32
	s_waitcnt lgkmcnt(6)
	v_fmac_f32_e32 v162, v53, v153
	v_fmac_f32_e32 v163, v37, v153
	ds_write2_b32 v176, v162, v163 offset0:128 offset1:160
	s_waitcnt lgkmcnt(6)
	v_fmac_f32_e32 v164, v5, v153
	v_fmac_f32_e32 v165, v21, v153
	ds_write2_b32 v177, v164, v165 offset0:192 offset1:224
	s_waitcnt lgkmcnt(6)
	v_fmac_f32_e32 v166, v102, v152
	v_fmac_f32_e32 v167, v118, v152
	ds_write2_b32 v154, v166, v167 offset0:0 offset1:32
	s_waitcnt lgkmcnt(6)
	v_fmac_f32_e32 v168, v70, v152
	v_fmac_f32_e32 v169, v86, v152
	ds_write2_b32 v179, v168, v169 offset0:64 offset1:96
	s_waitcnt lgkmcnt(6)
	v_fmac_f32_e32 v170, v38, v152
	v_fmac_f32_e32 v171, v54, v152
	ds_write2_b32 v180, v170, v171 offset0:128 offset1:160
	s_waitcnt lgkmcnt(6)
	v_fmac_f32_e32 v172, v22, v152
	v_fmac_f32_e32 v173, v6, v152
	ds_write2_b32 v181, v172, v173 offset0:192 offset1:224
	s_waitcnt lgkmcnt(6)
	v_fmac_f32_e32 v174, v103, v150
	v_fmac_f32_e32 v175, v119, v150
	ds_write2_b32 v182, v174, v175 offset0:0 offset1:32
	v_add_u32_e32 v176, 0x2400, v133
	ds_read2_b32 v[162:163], v176 offset0:64 offset1:96
	v_add_u32_e32 v177, 0x2400, v132
	ds_read2_b32 v[164:165], v177 offset0:128 offset1:160
	v_add_u32_e32 v178, 0x2400, v131
	ds_read2_b32 v[166:167], v178 offset0:192 offset1:224
	ds_read2_b32 v[168:169], v151 offset0:0 offset1:32
	v_add_u32_e32 v180, 0x2800, v138
	ds_read2_b32 v[170:171], v180 offset0:64 offset1:96
	v_add_u32_e32 v181, 0x2800, v137
	ds_read2_b32 v[172:173], v181 offset0:128 offset1:160
	v_add_u32_e32 v182, 0x2800, v136
	ds_read2_b32 v[174:175], v182 offset0:192 offset1:224
	s_waitcnt lgkmcnt(6)
	v_fmac_f32_e32 v162, v71, v150
	v_fmac_f32_e32 v163, v87, v150
	ds_write2_b32 v176, v162, v163 offset0:64 offset1:96
	s_waitcnt lgkmcnt(6)
	v_fmac_f32_e32 v164, v39, v150
	v_fmac_f32_e32 v165, v55, v150
	ds_write2_b32 v177, v164, v165 offset0:128 offset1:160
	s_waitcnt lgkmcnt(6)
; __device__ __forceinline__ void attn_unit(const bf16* __restrict__ qkvb, int seq, int q0, int h, ldsp_t ldsb, float* wsc, const float* tab, float lam) {
;     ...
;   asm volatile("s_waitcnt lgkmcnt(0)" ::: "memory"); __builtin_amdgcn_s_barrier(); asm volatile("" ::: "memory");
;   if (!mapw) {
; #pragma unroll
;     for (int r = 0; r < 16; ++r)
; #pragma unroll
;       for (int d = 0; d < 8; ++d) { const ldsf_t p_ = df + (((r & 3) + 8 * (r >> 2)) * 256 + ((d * 32 + r32) ^ ((d >> 1) << 2) ^ ((r & 3) << 4))); *p_ = *p_ + o[d][r] * rli[r]; }
;   }
	v_fmac_f32_e32 v166, v23, v150
	v_fmac_f32_e32 v167, v7, v150
	ds_write2_b32 v178, v166, v167 offset0:192 offset1:224
	s_waitcnt lgkmcnt(6)
	v_fmac_f32_e32 v168, v120, v149
	v_fmac_f32_e32 v169, v104, v149
	ds_write2_b32 v151, v168, v169 offset0:0 offset1:32
	s_waitcnt lgkmcnt(6)
	v_fmac_f32_e32 v170, v88, v149
	v_fmac_f32_e32 v171, v72, v149
	ds_write2_b32 v180, v170, v171 offset0:64 offset1:96
	s_waitcnt lgkmcnt(6)
	v_fmac_f32_e32 v172, v56, v149
	v_fmac_f32_e32 v173, v40, v149
	ds_write2_b32 v181, v172, v173 offset0:128 offset1:160
	s_waitcnt lgkmcnt(6)
	v_fmac_f32_e32 v174, v8, v149
	v_fmac_f32_e32 v175, v24, v149
	ds_write2_b32 v182, v174, v175 offset0:192 offset1:224
	v_add_u32_e32 v176, 0x2c00, v135
	ds_read2_b32 v[162:163], v176 offset0:0 offset1:32
	v_add_u32_e32 v177, 0x2c00, v133
	ds_read2_b32 v[164:165], v177 offset0:64 offset1:96
	v_add_u32_e32 v178, 0x2c00, v132
	ds_read2_b32 v[166:167], v178 offset0:128 offset1:160
	v_add_u32_e32 v179, 0x2c00, v131
	ds_read2_b32 v[168:169], v179 offset0:192 offset1:224
	ds_read2_b32 v[170:171], v148 offset0:0 offset1:32
	v_add_u32_e32 v181, 0x4000, v138
	ds_read2_b32 v[172:173], v181 offset0:64 offset1:96
	v_add_u32_e32 v182, 0x4000, v137
	ds_read2_b32 v[174:175], v182 offset0:128 offset1:160
	s_waitcnt lgkmcnt(6)
	v_fmac_f32_e32 v162, v121, v147
	v_fmac_f32_e32 v163, v105, v147
	ds_write2_b32 v176, v162, v163 offset0:0 offset1:32
	s_waitcnt lgkmcnt(6)
	v_fmac_f32_e32 v164, v89, v147
	v_fmac_f32_e32 v165, v73, v147
	ds_write2_b32 v177, v164, v165 offset0:64 offset1:96
	s_waitcnt lgkmcnt(6)
	v_fmac_f32_e32 v166, v57, v147
	v_fmac_f32_e32 v167, v41, v147
	ds_write2_b32 v178, v166, v167 offset0:128 offset1:160
	s_waitcnt lgkmcnt(6)
	v_fmac_f32_e32 v168, v9, v147
	v_fmac_f32_e32 v169, v25, v147
	ds_write2_b32 v179, v168, v169 offset0:192 offset1:224
	s_waitcnt lgkmcnt(6)
	v_fmac_f32_e32 v170, v106, v146
	v_fmac_f32_e32 v171, v122, v146
	ds_write2_b32 v148, v170, v171 offset0:0 offset1:32
	s_waitcnt lgkmcnt(6)
	v_fmac_f32_e32 v172, v74, v146
	v_fmac_f32_e32 v173, v90, v146
	ds_write2_b32 v181, v172, v173 offset0:64 offset1:96
	s_waitcnt lgkmcnt(6)
	v_fmac_f32_e32 v174, v42, v146
	v_fmac_f32_e32 v175, v58, v146
	ds_write2_b32 v182, v174, v175 offset0:128 offset1:160
	v_add_u32_e32 v176, 0x4000, v136
	ds_read2_b32 v[162:163], v176 offset0:192 offset1:224
	v_add_u32_e32 v177, 0x4400, v135
	ds_read2_b32 v[164:165], v177 offset0:0 offset1:32
	v_add_u32_e32 v178, 0x4400, v133
	ds_read2_b32 v[166:167], v178 offset0:64 offset1:96
	v_add_u32_e32 v179, 0x4400, v132
	ds_read2_b32 v[168:169], v179 offset0:128 offset1:160
	v_add_u32_e32 v180, 0x4400, v131
	ds_read2_b32 v[170:171], v180 offset0:192 offset1:224
	ds_read2_b32 v[172:173], v145 offset0:0 offset1:32
	v_add_u32_e32 v182, 0x4800, v138
	ds_read2_b32 v[174:175], v182 offset0:64 offset1:96
	s_waitcnt lgkmcnt(6)
	v_fmac_f32_e32 v162, v26, v146
	v_fmac_f32_e32 v163, v10, v146
	ds_write2_b32 v176, v162, v163 offset0:192 offset1:224
	s_waitcnt lgkmcnt(6)
	v_fmac_f32_e32 v164, v107, v144
	v_fmac_f32_e32 v165, v123, v144
	ds_write2_b32 v177, v164, v165 offset0:0 offset1:32
	s_waitcnt lgkmcnt(6)
	v_fmac_f32_e32 v166, v75, v144
	v_fmac_f32_e32 v167, v91, v144
	ds_write2_b32 v178, v166, v167 offset0:64 offset1:96
	s_waitcnt lgkmcnt(6)
	v_fmac_f32_e32 v168, v43, v144
	v_fmac_f32_e32 v169, v59, v144
	ds_write2_b32 v179, v168, v169 offset0:128 offset1:160
	s_waitcnt lgkmcnt(6)
	v_fmac_f32_e32 v170, v27, v144
	v_fmac_f32_e32 v171, v11, v144
	ds_write2_b32 v180, v170, v171 offset0:192 offset1:224
	s_waitcnt lgkmcnt(6)
	v_fmac_f32_e32 v172, v124, v143
	v_fmac_f32_e32 v173, v108, v143
	ds_write2_b32 v145, v172, v173 offset0:0 offset1:32
	s_waitcnt lgkmcnt(6)
	v_fmac_f32_e32 v174, v92, v143
	v_fmac_f32_e32 v175, v76, v143
	ds_write2_b32 v182, v174, v175 offset0:64 offset1:96
	v_add_u32_e32 v176, 0x4800, v137
	ds_read2_b32 v[162:163], v176 offset0:128 offset1:160
	v_add_u32_e32 v177, 0x4800, v136
	ds_read2_b32 v[164:165], v177 offset0:192 offset1:224
	v_add_u32_e32 v178, 0x4c00, v135
	ds_read2_b32 v[166:167], v178 offset0:0 offset1:32
	v_add_u32_e32 v179, 0x4c00, v133
	ds_read2_b32 v[168:169], v179 offset0:64 offset1:96
	v_add_u32_e32 v180, 0x4c00, v132
	ds_read2_b32 v[170:171], v180 offset0:128 offset1:160
	v_add_u32_e32 v181, 0x4c00, v131
	ds_read2_b32 v[172:173], v181 offset0:192 offset1:224
	ds_read2_b32 v[174:175], v1 offset0:0 offset1:32
	s_waitcnt lgkmcnt(6)
	v_fmac_f32_e32 v162, v60, v143
	v_fmac_f32_e32 v163, v44, v143
	ds_write2_b32 v176, v162, v163 offset0:128 offset1:160
	s_waitcnt lgkmcnt(6)
	v_fmac_f32_e32 v164, v12, v143
	v_fmac_f32_e32 v165, v28, v143
	ds_write2_b32 v177, v164, v165 offset0:192 offset1:224
	s_waitcnt lgkmcnt(6)
	v_fmac_f32_e32 v166, v125, v142
	v_fmac_f32_e32 v167, v109, v142
	ds_write2_b32 v178, v166, v167 offset0:0 offset1:32
	s_waitcnt lgkmcnt(6)
	v_fmac_f32_e32 v168, v93, v142
	v_fmac_f32_e32 v169, v77, v142
	ds_write2_b32 v179, v168, v169 offset0:64 offset1:96
	s_waitcnt lgkmcnt(6)
	v_fmac_f32_e32 v170, v61, v142
	v_fmac_f32_e32 v171, v45, v142
	ds_write2_b32 v180, v170, v171 offset0:128 offset1:160
	s_waitcnt lgkmcnt(6)
	v_fmac_f32_e32 v172, v13, v142
	v_fmac_f32_e32 v173, v29, v142
	ds_write2_b32 v181, v172, v173 offset0:192 offset1:224
	s_waitcnt lgkmcnt(6)
; #define LAS __attribute__((address_space(3)))
; __device__ __forceinline__ void attn_unit(const bf16* __restrict__ qkvb, int seq, int q0, int h, ldsp_t ldsb, float* wsc, const float* tab, float lam) {
;     ...
;   asm volatile("s_waitcnt lgkmcnt(0)" ::: "memory"); __builtin_amdgcn_s_barrier(); asm volatile("" ::: "memory");
;   if (!mapw) {
; #pragma unroll
;     for (int r = 0; r < 16; ++r)
; #pragma unroll
;       for (int d = 0; d < 8; ++d) { const ldsf_t p_ = df + (((r & 3) + 8 * (r >> 2)) * 256 + ((d * 32 + r32) ^ ((d >> 1) << 2) ^ ((r & 3) << 4))); *p_ = *p_ + o[d][r] * rli[r]; }
;   }
; __global__ void __launch_bounds__(NWAVES * 64, 2) fwd_kernel(Args args) {
;     ...
;                     const int row = F.tid >> 2, qd = F.tid & 3;
;                     const LAS float* drow = (const LAS float*)(F.lds + RING_OFF) + row * 256; const int sw = (qd << 2) ^ ((row & 3) << 4);
;                     f32x4 av[16]; float ssq = 0.f;
; #pragma unroll
;                     for (int j = 0; j < 16; ++j) { av[j] = *(const LAS f32x4*)(drow + ((qd * 64 + 4 * j) ^ sw)); ssq += (av[j].x * av[j].x + av[j].y * av[j].y) + (av[j].z * av[j].z + av[j].w * av[j].w); }
;                     ssq += __uint_as_float((unsigned)__builtin_amdgcn_ds_bpermute((F.lane ^ 1) << 2, (int)__float_as_uint(ssq)));
	v_fmac_f32_e32 v174, v110, v141
	v_fmac_f32_e32 v175, v126, v141
	ds_write2_b32 v1, v174, v175 offset0:0 offset1:32
	v_add_u32_e32 v176, 0x6000, v138
	ds_read2_b32 v[162:163], v176 offset0:64 offset1:96
	v_add_u32_e32 v177, 0x6000, v137
	ds_read2_b32 v[164:165], v177 offset0:128 offset1:160
	v_add_u32_e32 v178, 0x6000, v136
	ds_read2_b32 v[166:167], v178 offset0:192 offset1:224
	v_add_u32_e32 v179, 0x6400, v135
	ds_read2_b32 v[168:169], v179 offset0:0 offset1:32
	v_add_u32_e32 v180, 0x6400, v133
	ds_read2_b32 v[170:171], v180 offset0:64 offset1:96
	v_add_u32_e32 v181, 0x6400, v132
	ds_read2_b32 v[172:173], v181 offset0:128 offset1:160
	v_add_u32_e32 v182, 0x6400, v131
	ds_read2_b32 v[174:175], v182 offset0:192 offset1:224
	s_waitcnt lgkmcnt(6)
	v_fmac_f32_e32 v162, v78, v141
	v_fmac_f32_e32 v163, v94, v141
	ds_write2_b32 v176, v162, v163 offset0:64 offset1:96
	s_waitcnt lgkmcnt(6)
	v_fmac_f32_e32 v164, v46, v141
	v_fmac_f32_e32 v165, v62, v141
	ds_write2_b32 v177, v164, v165 offset0:128 offset1:160
	s_waitcnt lgkmcnt(6)
	v_fmac_f32_e32 v166, v30, v141
	v_fmac_f32_e32 v167, v14, v141
	ds_write2_b32 v178, v166, v167 offset0:192 offset1:224
	s_waitcnt lgkmcnt(6)
	v_fmac_f32_e32 v168, v111, v139
	v_fmac_f32_e32 v169, v127, v139
	ds_write2_b32 v179, v168, v169 offset0:0 offset1:32
	s_waitcnt lgkmcnt(6)
	v_fmac_f32_e32 v170, v79, v139
	v_fmac_f32_e32 v171, v95, v139
	ds_write2_b32 v180, v170, v171 offset0:64 offset1:96
	s_waitcnt lgkmcnt(6)
	v_fmac_f32_e32 v172, v47, v139
	v_fmac_f32_e32 v173, v63, v139
	ds_write2_b32 v181, v172, v173 offset0:128 offset1:160
	s_waitcnt lgkmcnt(6)
	v_fmac_f32_e32 v174, v31, v139
	v_fmac_f32_e32 v175, v15, v139
	ds_write2_b32 v182, v174, v175 offset0:192 offset1:224
	ds_read2_b32 v[162:163], v140 offset0:0 offset1:32
	v_add_u32_e32 v177, 0x6800, v138
	ds_read2_b32 v[164:165], v177 offset0:64 offset1:96
	v_add_u32_e32 v178, 0x6800, v137
	ds_read2_b32 v[166:167], v178 offset0:128 offset1:160
	v_add_u32_e32 v179, 0x6800, v136
	ds_read2_b32 v[168:169], v179 offset0:192 offset1:224
	v_add_u32_e32 v180, 0x6c00, v135
	ds_read2_b32 v[170:171], v180 offset0:0 offset1:32
	v_add_u32_e32 v181, 0x6c00, v133
	ds_read2_b32 v[172:173], v181 offset0:64 offset1:96
	v_add_u32_e32 v182, 0x6c00, v132
	ds_read2_b32 v[174:175], v182 offset0:128 offset1:160
	s_waitcnt lgkmcnt(6)
	v_fmac_f32_e32 v162, v128, v134
	v_fmac_f32_e32 v163, v112, v134
	ds_write2_b32 v140, v162, v163 offset0:0 offset1:32
	s_waitcnt lgkmcnt(6)
	v_fmac_f32_e32 v164, v96, v134
	v_fmac_f32_e32 v165, v80, v134
	ds_write2_b32 v177, v164, v165 offset0:64 offset1:96
	s_waitcnt lgkmcnt(6)
	v_fmac_f32_e32 v166, v64, v134
	v_fmac_f32_e32 v167, v48, v134
	ds_write2_b32 v178, v166, v167 offset0:128 offset1:160
	s_waitcnt lgkmcnt(6)
	v_fmac_f32_e32 v168, v16, v134
	v_fmac_f32_e32 v169, v32, v134
	ds_write2_b32 v179, v168, v169 offset0:192 offset1:224
	s_waitcnt lgkmcnt(6)
	v_fmac_f32_e32 v170, v129, v130
	v_fmac_f32_e32 v171, v113, v130
	ds_write2_b32 v180, v170, v171 offset0:0 offset1:32
	s_waitcnt lgkmcnt(6)
	v_fmac_f32_e32 v172, v97, v130
	v_fmac_f32_e32 v173, v81, v130
	ds_write2_b32 v181, v172, v173 offset0:64 offset1:96
	s_waitcnt lgkmcnt(6)
	v_fmac_f32_e32 v174, v65, v130
	v_fmac_f32_e32 v175, v49, v130
	ds_write2_b32 v182, v174, v175 offset0:128 offset1:160
	v_add_u32_e32 v176, 0x6c00, v131
	ds_read2_b32 v[162:163], v176 offset0:192 offset1:224
	s_waitcnt lgkmcnt(0)
	v_fmac_f32_e32 v162, v17, v130
	v_fmac_f32_e32 v163, v33, v130
	ds_write2_b32 v176, v162, v163 offset0:192 offset1:224
.LBB0_588:
	v_mov_b32_e32 v67, v245
	s_waitcnt vmcnt(0) lgkmcnt(0)
	s_barrier
	v_bfrev_b32_e32 v0, 0.5
	v_ashrrev_i32_e32 v66, 2, v67
	v_and_b32_e32 v1, 3, v67
	v_lshlrev_b32_e32 v3, 2, v1
	v_lshlrev_b32_e32 v4, 4, v66
	v_and_or_b32 v3, v4, 48, v3
	v_lshl_add_u32 v2, v66, 10, 0
	v_lshlrev_b32_e32 v75, 8, v1
	v_lshlrev_b32_e32 v5, 2, v3
	v_lshlrev_b32_e32 v4, 6, v1
	v_add3_u32 v5, v2, v75, v5
	ds_read_b128 v[22:25], v5
	v_bitop3_b32 v5, v4, v3, 4 bitop3:0x36
	v_lshl_add_u32 v5, v5, 2, v2
	ds_read_b128 v[38:41], v5
	v_bitop3_b32 v5, v4, v3, 8 bitop3:0x36
	v_lshl_add_u32 v5, v5, 2, v2
	ds_read_b128 v[26:29], v5
	v_bitop3_b32 v5, v4, v3, 12 bitop3:0x36
	v_lshl_add_u32 v5, v5, 2, v2
	ds_read_b128 v[34:37], v5
	s_waitcnt lgkmcnt(3)
	v_pk_mul_f32 v[6:7], v[24:25], v[24:25]
	v_pk_mul_f32 v[8:9], v[22:23], v[22:23]
	v_lshlrev_b32_e32 v67, 2, v67
	v_pk_mov_b32 v[10:11], v[8:9], v[6:7] op_sel:[1,0]
	v_mov_b32_e32 v9, v7
	v_pk_add_f32 v[6:7], v[10:11], v[8:9]
	s_waitcnt lgkmcnt(0)
	v_mul_f32_e32 v5, v34, v34
	v_pk_add_f32 v[6:7], v[6:7], v[6:7] op_sel:[0,1] op_sel_hi:[1,0]
	v_pk_mul_f32 v[8:9], v[40:41], v[40:41]
	v_pk_mul_f32 v[10:11], v[38:39], v[38:39]
	v_mov_b32_e32 v7, v5
	v_bitop3_b32 v5, v4, v3, 16 bitop3:0x36
	v_pk_mov_b32 v[12:13], v[10:11], v[8:9] op_sel:[1,0]
	v_mov_b32_e32 v11, v9
	v_lshl_add_u32 v5, v5, 2, v2
	v_pk_add_f32 v[8:9], v[12:13], v[10:11]
	ds_read_b128 v[30:33], v5
	v_bitop3_b32 v5, v4, v3, 20 bitop3:0x36
	v_mul_f32_e32 v10, v35, v35
	v_pk_add_f32 v[8:9], v[8:9], v[8:9] op_sel:[0,1] op_sel_hi:[1,0]
	v_lshl_add_u32 v5, v5, 2, v2
	v_mov_b32_e32 v9, v10
	ds_read_b128 v[42:45], v5
	v_bitop3_b32 v5, v4, v3, 24 bitop3:0x36
	v_pk_add_f32 v[6:7], v[6:7], v[8:9]
	v_mul_f32_e32 v8, v27, v27
	v_lshl_add_u32 v5, v5, 2, v2
	v_mul_f32_e32 v11, v36, v36
	v_pk_fma_f32 v[8:9], v[26:27], v[26:27], v[8:9] op_sel_hi:[1,1,0]
	v_mul_f32_e32 v10, v29, v29
	ds_read_b128 v[18:21], v5
	v_mul_f32_e32 v12, v37, v37
	v_mov_b32_e32 v9, v11
	v_pk_fma_f32 v[10:11], v[28:29], v[28:29], v[10:11] op_sel_hi:[1,1,0]
	s_mov_b32 s8, s63
	v_mov_b32_e32 v11, v12
	v_pk_add_f32 v[8:9], v[8:9], v[10:11]
	s_waitcnt lgkmcnt(2)
; #define LAS __attribute__((address_space(3)))
; #define KIN(i) ((const float*)karg(i))
; __global__ void __launch_bounds__(NWAVES * 64, 2) fwd_kernel(Args args) {
;     ...
;                     const int row = F.tid >> 2, qd = F.tid & 3;
;                     const LAS float* drow = (const LAS float*)(F.lds + RING_OFF) + row * 256; const int sw = (qd << 2) ^ ((row & 3) << 4);
;                     f32x4 av[16]; float ssq = 0.f;
; #pragma unroll
;                     for (int j = 0; j < 16; ++j) { av[j] = *(const LAS f32x4*)(drow + ((qd * 64 + 4 * j) ^ sw)); ssq += (av[j].x * av[j].x + av[j].y * av[j].y) + (av[j].z * av[j].z + av[j].w * av[j].w); }
;                     ssq += __uint_as_float((unsigned)__builtin_amdgcn_ds_bpermute((F.lane ^ 1) << 2, (int)__float_as_uint(ssq)));
;                     ssq += __uint_as_float((unsigned)__builtin_amdgcn_ds_bpermute((F.lane ^ 2) << 2, (int)__float_as_uint(ssq)));
;                     int lq = l; asm volatile("" : "+s"(lq));
;                     const float oml = lq == 0 ? 0.8f : 0.64449093240903074f;
;                     const float rs = oml / sqrtf(ssq * (1.0f / 256.0f) + LN_EPS);
;                     const f32x4* sg = (const f32x4*)(KIN(8) + lq * 256 + qd * 64);
;                     bf16* orow = P_OB + ((size_t)b * S + qb * 128 + row) * DM + h * 256 + qd * 64;
	v_pk_mul_f32 v[10:11], v[30:31], v[30:31]
	v_pk_add_f32 v[6:7], v[6:7], v[8:9]
	v_pk_mul_f32 v[8:9], v[32:33], v[32:33]
	s_waitcnt lgkmcnt(0)
	v_mul_f32_e32 v5, v18, v18
	v_pk_add_f32 v[6:7], v[6:7], v[6:7] op_sel:[0,1] op_sel_hi:[1,0]
	v_pk_mov_b32 v[12:13], v[10:11], v[8:9] op_sel:[1,0]
	v_mov_b32_e32 v11, v9
	v_mov_b32_e32 v7, v5
	v_bitop3_b32 v5, v4, v3, 28 bitop3:0x36
	v_pk_add_f32 v[8:9], v[12:13], v[10:11]
	v_lshl_add_u32 v5, v5, 2, v2
	v_mul_f32_e32 v10, v19, v19
	v_pk_add_f32 v[8:9], v[8:9], v[8:9] op_sel:[0,1] op_sel_hi:[1,0]
	ds_read_b128 v[62:65], v5
	v_bitop3_b32 v5, v4, v3, 32 bitop3:0x36
	v_mov_b32_e32 v9, v10
	v_lshl_add_u32 v5, v5, 2, v2
	v_pk_add_f32 v[6:7], v[6:7], v[8:9]
	v_mul_f32_e32 v8, v43, v43
	ds_read_b128 v[58:61], v5
	v_bitop3_b32 v5, v4, v3, 36 bitop3:0x36
	v_mul_f32_e32 v11, v20, v20
	v_pk_fma_f32 v[8:9], v[42:43], v[42:43], v[8:9] op_sel_hi:[1,1,0]
	v_mul_f32_e32 v10, v45, v45
	v_lshl_add_u32 v5, v5, 2, v2
	v_mul_f32_e32 v12, v21, v21
	v_mov_b32_e32 v9, v11
	v_pk_fma_f32 v[10:11], v[44:45], v[44:45], v[10:11] op_sel_hi:[1,1,0]
	ds_read_b128 v[54:57], v5
	v_mov_b32_e32 v11, v12
	v_pk_add_f32 v[8:9], v[8:9], v[10:11]
	s_waitcnt lgkmcnt(2)
	v_pk_mul_f32 v[10:11], v[62:63], v[62:63]
	v_pk_add_f32 v[6:7], v[6:7], v[8:9]
	v_pk_mul_f32 v[8:9], v[64:65], v[64:65]
	s_waitcnt lgkmcnt(0)
	v_mul_f32_e32 v5, v54, v54
	v_pk_mov_b32 v[12:13], v[10:11], v[8:9] op_sel:[1,0]
	v_mov_b32_e32 v11, v9
	v_pk_add_f32 v[8:9], v[12:13], v[10:11]
	v_pk_add_f32 v[6:7], v[6:7], v[6:7] op_sel:[0,1] op_sel_hi:[1,0]
	v_mul_f32_e32 v10, v55, v55
	v_mov_b32_e32 v7, v5
	v_pk_add_f32 v[8:9], v[8:9], v[8:9] op_sel:[0,1] op_sel_hi:[1,0]
	v_bitop3_b32 v5, v4, v3, 40 bitop3:0x36
	v_mov_b32_e32 v9, v10
	v_lshl_add_u32 v5, v5, 2, v2
	v_pk_add_f32 v[6:7], v[6:7], v[8:9]
	v_mul_f32_e32 v8, v59, v59
	ds_read_b128 v[50:53], v5
	v_mul_f32_e32 v11, v56, v56
	v_pk_fma_f32 v[8:9], v[58:59], v[58:59], v[8:9] op_sel_hi:[1,1,0]
	v_mul_f32_e32 v10, v61, v61
	v_mul_f32_e32 v12, v57, v57
	v_mov_b32_e32 v9, v11
	v_pk_fma_f32 v[10:11], v[60:61], v[60:61], v[10:11] op_sel_hi:[1,1,0]
	v_bitop3_b32 v5, v4, v3, 44 bitop3:0x36
	v_mov_b32_e32 v11, v12
	v_pk_add_f32 v[8:9], v[8:9], v[10:11]
	v_lshl_add_u32 v5, v5, 2, v2
	v_pk_add_f32 v[6:7], v[6:7], v[8:9]
	s_waitcnt lgkmcnt(0)
	v_pk_mul_f32 v[8:9], v[52:53], v[52:53]
	v_pk_mul_f32 v[10:11], v[50:51], v[50:51]
	ds_read_b128 v[46:49], v5
	v_bitop3_b32 v5, v4, v3, 48 bitop3:0x36
	v_pk_mov_b32 v[12:13], v[10:11], v[8:9] op_sel:[1,0]
	v_mov_b32_e32 v11, v9
	v_lshl_add_u32 v5, v5, 2, v2
	v_pk_add_f32 v[8:9], v[12:13], v[10:11]
	ds_read_b128 v[10:13], v5
	v_pk_add_f32 v[6:7], v[6:7], v[6:7] op_sel:[0,1] op_sel_hi:[1,0]
	v_pk_add_f32 v[8:9], v[8:9], v[8:9] op_sel:[0,1] op_sel_hi:[1,0]
	v_lshlrev_b32_e32 v226, 7, v1
	v_mov_b32_e32 v79, v24
	s_waitcnt lgkmcnt(0)
	v_mul_f32_e32 v5, v10, v10
	v_mul_f32_e32 v14, v11, v11
	v_mov_b32_e32 v7, v5
	v_mov_b32_e32 v9, v14
	v_pk_add_f32 v[6:7], v[6:7], v[8:9]
	v_mul_f32_e32 v8, v47, v47
	v_mul_f32_e32 v15, v12, v12
	v_pk_fma_f32 v[8:9], v[46:47], v[46:47], v[8:9] op_sel_hi:[1,1,0]
	v_mul_f32_e32 v14, v49, v49
	v_mul_f32_e32 v16, v13, v13
	v_mov_b32_e32 v9, v15
	v_pk_fma_f32 v[14:15], v[48:49], v[48:49], v[14:15] op_sel_hi:[1,1,0]
	v_bitop3_b32 v5, v4, v3, 52 bitop3:0x36
	v_mov_b32_e32 v15, v16
	v_lshl_add_u32 v5, v5, 2, v2
	v_pk_add_f32 v[8:9], v[8:9], v[14:15]
	ds_read_b128 v[14:17], v5
	v_pk_add_f32 v[68:69], v[6:7], v[8:9]
	v_bitop3_b32 v5, v4, v3, 56 bitop3:0x36
	v_bitop3_b32 v3, v4, v3, 60 bitop3:0x36
	v_lshl_add_u32 v5, v5, 2, v2
	s_waitcnt lgkmcnt(0)
	v_pk_mul_f32 v[6:7], v[16:17], v[16:17]
	v_pk_mul_f32 v[8:9], v[14:15], v[14:15]
	v_lshl_add_u32 v2, v3, 2, v2
	v_pk_mov_b32 v[70:71], v[8:9], v[6:7] op_sel:[1,0]
	v_mov_b32_e32 v9, v7
	v_pk_add_f32 v[70:71], v[70:71], v[8:9]
	ds_read_b128 v[6:9], v5
	ds_read_b128 v[2:5], v2
	v_pk_add_f32 v[68:69], v[68:69], v[68:69] op_sel:[0,1] op_sel_hi:[1,0]
	v_pk_add_f32 v[70:71], v[70:71], v[70:71] op_sel:[0,1] op_sel_hi:[1,0]
	s_cmp_eq_u32 s8, 0
	s_waitcnt lgkmcnt(0)
	v_mul_f32_e32 v72, v2, v2
	v_mul_f32_e32 v73, v3, v3
	v_mov_b32_e32 v69, v72
	v_mov_b32_e32 v71, v73
	v_pk_add_f32 v[68:69], v[68:69], v[70:71]
	v_mul_f32_e32 v70, v7, v7
	v_mul_f32_e32 v72, v9, v9
	v_mul_f32_e32 v74, v4, v4
	v_mul_f32_e32 v76, v5, v5
	v_pk_fma_f32 v[70:71], v[6:7], v[6:7], v[70:71] op_sel_hi:[1,1,0]
	v_pk_fma_f32 v[72:73], v[8:9], v[8:9], v[72:73] op_sel_hi:[1,1,0]
	v_mov_b32_e32 v71, v74
	v_mov_b32_e32 v73, v76
	v_pk_add_f32 v[70:71], v[70:71], v[72:73]
	s_cselect_b64 vcc, -1, 0
	v_pk_add_f32 v[68:69], v[68:69], v[70:71]
	v_mov_b32_e32 v24, v23
	v_add_f32_e32 v68, v68, v69
	v_bitop3_b32 v69, v67, 4, v0 bitop3:0x6c
	ds_bpermute_b32 v69, v69, v68
	v_bitop3_b32 v67, v67, 8, v0 bitop3:0x6c
	v_mov_b32_e32 v78, v22
	s_waitcnt lgkmcnt(0)
	v_add_f32_e32 v68, v68, v69
	ds_bpermute_b32 v67, v67, v68
	v_mov_b32_e32 v69, 0x3f4ccccd
	s_waitcnt lgkmcnt(0)
	v_add_f32_e32 v67, v68, v67
	v_mov_b32_e32 v68, 0x3f24fd5c
	v_fmamk_f32 v67, v67, 0x3b800000, v244
	v_cndmask_b32_e32 v68, v68, v69, vcc
	v_cmp_gt_f32_e32 vcc, s47, v67
	v_mul_f32_e32 v69, 0x4f800000, v67
	s_nop 0
	v_cndmask_b32_e32 v67, v67, v69, vcc
	v_sqrt_f32_e32 v69, v67
	s_nop 0
	v_add_u32_e32 v70, -1, v69
	v_fma_f32 v71, -v70, v69, v67
	v_cmp_ge_f32_e64 s[4:5], 0, v71
	v_add_u32_e32 v71, 1, v69
	s_nop 0
	v_cndmask_b32_e64 v70, v69, v70, s[4:5]
	v_fma_f32 v69, -v71, v69, v67
	v_cmp_lt_f32_e64 s[4:5], 0, v69
	s_nop 1
	v_cndmask_b32_e64 v69, v70, v71, s[4:5]
	v_mul_f32_e32 v70, 0x37800000, v69
	v_cndmask_b32_e32 v69, v69, v70, vcc
	v_cmp_class_f32_e32 vcc, v67, v246
	s_nop 1
	v_cndmask_b32_e32 v67, v69, v67, vcc
	v_div_scale_f32 v69, s[4:5], v67, v67, v68
	s_mov_b32 s4, 8
	s_ashr_i32 s5, s4, 31
	s_lshl_b64 s[4:5], s[4:5], 3
	s_add_u32 s4, s0, s4
	s_addc_u32 s5, s1, s5
	s_load_dwordx2 s[4:5], s[4:5], 0x0
	v_rcp_f32_e32 v70, v69
	s_lshl_b32 s8, s8, 8
	s_ashr_i32 s9, s8, 31
	s_lshl_b64 s[8:9], s[8:9], 2
	v_fma_f32 v71, -v69, v70, 1.0
	s_waitcnt lgkmcnt(0)
; __device__ __forceinline__ unsigned pk2(float lo, float hi) { return f2bf(lo) | (f2bf(hi) << 16); }
; #define KIN(i) ((const float*)karg(i))
; __global__ void __launch_bounds__(NWAVES * 64, 2) fwd_kernel(Args args) {
;     ...
;                     const float rs = oml / sqrtf(ssq * (1.0f / 256.0f) + LN_EPS);
;                     const f32x4* sg = (const f32x4*)(KIN(8) + lq * 256 + qd * 64);
;                     bf16* orow = P_OB + ((size_t)b * S + qb * 128 + row) * DM + h * 256 + qd * 64;
; #pragma unroll
;                     for (int j = 0; j < 8; ++j) { const f32x4 a = av[2 * j], c2 = av[2 * j + 1], g0 = sg[2 * j], g1 = sg[2 * j + 1];
;                         v4u w; w.x = pk2(a.x * rs * g0.x, a.y * rs * g0.y); w.y = pk2(a.z * rs * g0.z, a.w * rs * g0.w); w.z = pk2(c2.x * rs * g1.x, c2.y * rs * g1.y); w.w = pk2(c2.z * rs * g1.z, c2.w * rs * g1.w);
;                         *(v4u*)(orow + 8 * j) = w; }
	s_add_u32 s4, s4, s8
	s_mov_b32 s8, 26
	v_fmac_f32_e32 v70, v71, v70
	v_div_scale_f32 v71, vcc, v68, v67, v68
	s_addc_u32 s5, s5, s9
	s_ashr_i32 s9, s8, 31
	v_mul_f32_e32 v72, v71, v70
	s_lshl_b64 s[8:9], s[8:9], 3
	v_fma_f32 v73, -v69, v72, v71
	s_add_u32 s8, s0, s8
	v_fmac_f32_e32 v72, v73, v70
	s_addc_u32 s9, s1, s9
	v_fma_f32 v69, -v69, v72, v71
	s_load_dwordx2 s[8:9], s[8:9], 0x0
	v_div_fmas_f32 v69, v69, v70, v72
	s_add_u32 s6, s6, s14
	v_div_fixup_f32 v74, v69, v67, v68
	s_addc_u32 s7, s7, 0
	v_ashrrev_i32_e32 v67, 31, v66
	v_lshl_add_u64 v[66:67], s[6:7], 0, v[66:67]
	v_lshlrev_b64 v[66:67], 12, v[66:67]
	s_waitcnt lgkmcnt(0)
	v_lshl_add_u64 v[66:67], s[8:9], 0, v[66:67]
	s_lshl_b32 s84, s15, 1
	v_lshl_add_u64 v[66:67], v[66:67], 0, s[84:85]
	v_lshl_add_u64 v[76:77], v[66:67], 0, v[226:227]
	global_load_dwordx4 v[112:115], v75, s[4:5] offset:16
	global_load_dwordx4 v[116:119], v75, s[4:5]
	global_load_dwordx4 v[120:123], v75, s[4:5] offset:48
	global_load_dwordx4 v[124:127], v75, s[4:5] offset:32
	global_load_dwordx4 v[128:131], v75, s[4:5] offset:80
	global_load_dwordx4 v[132:135], v75, s[4:5] offset:64
	global_load_dwordx4 v[136:139], v75, s[4:5] offset:112
	global_load_dwordx4 v[140:143], v75, s[4:5] offset:96
	global_load_dwordx4 v[144:147], v75, s[4:5] offset:144
	global_load_dwordx4 v[148:151], v75, s[4:5] offset:128
	global_load_dwordx4 v[152:155], v75, s[4:5] offset:176
	global_load_dwordx4 v[156:159], v75, s[4:5] offset:160
	global_load_dwordx4 v[160:163], v75, s[4:5] offset:208
	global_load_dwordx4 v[164:167], v75, s[4:5] offset:192
	global_load_dwordx4 v[168:171], v75, s[4:5] offset:240
	global_load_dwordx4 v[172:175], v75, s[4:5] offset:224
	v_pk_mul_f32 v[22:23], v[74:75], v[24:25] op_sel_hi:[0,1]
	v_mov_b32_e32 v25, v40
	v_mov_b32_e32 v40, v39
	v_mov_b32_e32 v24, v38
	v_pk_mul_f32 v[38:39], v[74:75], v[40:41] op_sel_hi:[0,1]
	v_pk_mul_f32 v[78:79], v[74:75], v[78:79] op_sel_hi:[0,1]
	v_pk_mul_f32 v[24:25], v[74:75], v[24:25] op_sel_hi:[0,1]
	s_add_i32 s13, s13, 1
	s_cmp_eq_u32 s13, 4
	s_waitcnt vmcnt(14)
	v_mov_b64_e32 v[66:67], v[112:113]
	v_mov_b64_e32 v[68:69], v[114:115]
	v_mov_b64_e32 v[70:71], v[116:117]
	v_mov_b64_e32 v[72:73], v[118:119]
	v_mov_b32_e32 v81, v72
	v_mov_b32_e32 v72, v71
	v_mov_b32_e32 v71, v68
	v_mov_b32_e32 v68, v67
	v_mov_b32_e32 v80, v70
	v_pk_mul_f32 v[22:23], v[22:23], v[72:73]
	v_mov_b32_e32 v70, v66
	v_pk_mul_f32 v[38:39], v[38:39], v[68:69]
	v_pk_mul_f32 v[78:79], v[78:79], v[80:81]
	v_pk_mul_f32 v[24:25], v[24:25], v[70:71]
	v_bfe_u32 v1, v39, 16, 1
	v_bfe_u32 v40, v38, 16, 1
	v_bfe_u32 v41, v23, 16, 1
	v_bfe_u32 v66, v22, 16, 1
	v_add3_u32 v22, v22, v66, s72
	v_add3_u32 v23, v23, v41, s72
	v_add3_u32 v38, v38, v40, s72
	v_add3_u32 v1, v39, v1, s72
	v_bfe_u32 v39, v78, 16, 1
	v_bfe_u32 v40, v79, 16, 1
	v_bfe_u32 v41, v24, 16, 1
	v_bfe_u32 v66, v25, 16, 1
	v_add3_u32 v25, v25, v66, s72
	v_add3_u32 v24, v24, v41, s72
	v_add3_u32 v40, v79, v40, s72
	v_add3_u32 v39, v78, v39, s72
	v_lshrrev_b32_e32 v39, 16, v39
	v_lshrrev_b32_e32 v40, 16, v40
	v_lshrrev_b32_e32 v24, 16, v24
	v_lshrrev_b32_e32 v25, 16, v25
	v_and_or_b32 v25, v1, s46, v25
	v_and_or_b32 v24, v38, s46, v24
	v_and_or_b32 v23, v23, s46, v40
	v_and_or_b32 v22, v22, s46, v39
	global_store_dwordx4 v[76:77], v[22:25], off
	v_mov_b32_e32 v67, v28
	v_mov_b32_e32 v28, v27
	v_mov_b32_e32 v66, v26
	v_pk_mul_f32 v[26:27], v[74:75], v[28:29] op_sel_hi:[0,1]
	v_mov_b32_e32 v29, v36
	v_mov_b32_e32 v36, v35
	v_mov_b32_e32 v28, v34
	v_pk_mul_f32 v[34:35], v[74:75], v[36:37] op_sel_hi:[0,1]
	v_pk_mul_f32 v[66:67], v[74:75], v[66:67] op_sel_hi:[0,1]
	v_pk_mul_f32 v[28:29], v[74:75], v[28:29] op_sel_hi:[0,1]
	s_waitcnt vmcnt(12)
	v_mov_b64_e32 v[22:23], v[120:121]
	v_mov_b64_e32 v[24:25], v[122:123]
	v_mov_b64_e32 v[38:39], v[124:125]
	v_mov_b64_e32 v[40:41], v[126:127]
	v_mov_b32_e32 v69, v40
	v_mov_b32_e32 v40, v39
	v_mov_b32_e32 v39, v24
	v_mov_b32_e32 v24, v23
	v_mov_b32_e32 v68, v38
	v_pk_mul_f32 v[26:27], v[26:27], v[40:41]
	v_mov_b32_e32 v38, v22
	v_pk_mul_f32 v[22:23], v[34:35], v[24:25]
	v_pk_mul_f32 v[66:67], v[66:67], v[68:69]
	v_pk_mul_f32 v[28:29], v[28:29], v[38:39]
	v_bfe_u32 v1, v23, 16, 1
	v_bfe_u32 v24, v22, 16, 1
	v_bfe_u32 v25, v27, 16, 1
	v_bfe_u32 v34, v26, 16, 1
	v_add3_u32 v26, v26, v34, s72
	v_add3_u32 v27, v27, v25, s72
	v_add3_u32 v22, v22, v24, s72
	v_add3_u32 v1, v23, v1, s72
	v_bfe_u32 v23, v66, 16, 1
	v_bfe_u32 v24, v67, 16, 1
	v_bfe_u32 v25, v28, 16, 1
	v_bfe_u32 v34, v29, 16, 1
	v_add3_u32 v29, v29, v34, s72
	v_add3_u32 v25, v28, v25, s72
	v_add3_u32 v24, v67, v24, s72
	v_add3_u32 v23, v66, v23, s72
	v_lshrrev_b32_e32 v28, 16, v23
	v_lshrrev_b32_e32 v23, 16, v24
	v_lshrrev_b32_e32 v24, 16, v25
	v_lshrrev_b32_e32 v25, 16, v29
	v_and_or_b32 v25, v1, s46, v25
	v_and_or_b32 v24, v22, s46, v24
	v_and_or_b32 v23, v27, s46, v23
	v_and_or_b32 v22, v26, s46, v28
	global_store_dwordx4 v[76:77], v[22:25], off offset:16
	v_mov_b32_e32 v35, v32
	v_mov_b32_e32 v32, v31
	v_mov_b32_e32 v34, v30
	v_pk_mul_f32 v[30:31], v[74:75], v[32:33] op_sel_hi:[0,1]
	v_pk_mul_f32 v[34:35], v[74:75], v[34:35] op_sel_hi:[0,1]
	s_waitcnt vmcnt(10)
; __device__ __forceinline__ unsigned pk2(float lo, float hi) { return f2bf(lo) | (f2bf(hi) << 16); }
; __global__ void __launch_bounds__(NWAVES * 64, 2) fwd_kernel(Args args) {
;     ...
;                     for (int j = 0; j < 8; ++j) { const f32x4 a = av[2 * j], c2 = av[2 * j + 1], g0 = sg[2 * j], g1 = sg[2 * j + 1];
;                         v4u w; w.x = pk2(a.x * rs * g0.x, a.y * rs * g0.y); w.y = pk2(a.z * rs * g0.z, a.w * rs * g0.w); w.z = pk2(c2.x * rs * g1.x, c2.y * rs * g1.y); w.w = pk2(c2.z * rs * g1.z, c2.w * rs * g1.w);
;                         *(v4u*)(orow + 8 * j) = w; }
	v_mov_b64_e32 v[22:23], v[128:129]
	v_mov_b64_e32 v[24:25], v[130:131]
	v_mov_b64_e32 v[26:27], v[132:133]
	v_mov_b64_e32 v[28:29], v[134:135]
	v_mov_b32_e32 v37, v28
	v_mov_b32_e32 v28, v27
	v_mov_b32_e32 v36, v26
	v_pk_mul_f32 v[26:27], v[30:31], v[28:29]
	v_mov_b32_e32 v28, v42
	v_mov_b32_e32 v29, v44
	v_pk_mul_f32 v[28:29], v[74:75], v[28:29] op_sel_hi:[0,1]
	v_mov_b32_e32 v30, v22
	v_mov_b32_e32 v31, v24
	v_mov_b32_e32 v44, v43
	v_pk_mul_f32 v[28:29], v[28:29], v[30:31]
	v_pk_mul_f32 v[30:31], v[74:75], v[44:45] op_sel_hi:[0,1]
	v_mov_b32_e32 v24, v23
	v_pk_mul_f32 v[22:23], v[30:31], v[24:25]
	v_pk_mul_f32 v[34:35], v[34:35], v[36:37]
	v_bfe_u32 v1, v23, 16, 1
	v_bfe_u32 v24, v22, 16, 1
	v_bfe_u32 v25, v27, 16, 1
	v_bfe_u32 v30, v26, 16, 1
	v_add3_u32 v26, v26, v30, s72
	v_add3_u32 v27, v27, v25, s72
	v_add3_u32 v22, v22, v24, s72
	v_add3_u32 v1, v23, v1, s72
	v_bfe_u32 v23, v34, 16, 1
	v_bfe_u32 v24, v35, 16, 1
	v_bfe_u32 v25, v28, 16, 1
	v_bfe_u32 v30, v29, 16, 1
	v_add3_u32 v29, v29, v30, s72
	v_add3_u32 v25, v28, v25, s72
	v_add3_u32 v24, v35, v24, s72
	v_add3_u32 v23, v34, v23, s72
	v_lshrrev_b32_e32 v28, 16, v23
	v_lshrrev_b32_e32 v23, 16, v24
	v_lshrrev_b32_e32 v24, 16, v25
	v_lshrrev_b32_e32 v25, 16, v29
	v_and_or_b32 v25, v1, s46, v25
	v_and_or_b32 v24, v22, s46, v24
	v_and_or_b32 v23, v27, s46, v23
	v_and_or_b32 v22, v26, s46, v28
	global_store_dwordx4 v[76:77], v[22:25], off offset:32
	v_mov_b32_e32 v31, v20
	v_mov_b32_e32 v20, v19
	v_mov_b32_e32 v30, v18
	v_pk_mul_f32 v[18:19], v[74:75], v[20:21] op_sel_hi:[0,1]
	v_mov_b32_e32 v20, v62
	v_mov_b32_e32 v21, v64
	v_pk_mul_f32 v[20:21], v[74:75], v[20:21] op_sel_hi:[0,1]
	v_mov_b32_e32 v64, v63
	v_pk_mul_f32 v[30:31], v[74:75], v[30:31] op_sel_hi:[0,1]
	s_waitcnt vmcnt(8)
	v_mov_b64_e32 v[22:23], v[136:137]
	v_mov_b64_e32 v[24:25], v[138:139]
	v_mov_b64_e32 v[26:27], v[140:141]
	v_mov_b64_e32 v[28:29], v[142:143]
	v_mov_b32_e32 v32, v26
	v_mov_b32_e32 v33, v28
	v_mov_b32_e32 v28, v27
	v_mov_b32_e32 v26, v22
	v_mov_b32_e32 v27, v24
	v_pk_mul_f32 v[20:21], v[20:21], v[26:27]
	v_pk_mul_f32 v[26:27], v[74:75], v[64:65] op_sel_hi:[0,1]
	v_mov_b32_e32 v24, v23
	v_pk_mul_f32 v[18:19], v[18:19], v[28:29]
	v_pk_mul_f32 v[22:23], v[26:27], v[24:25]
	v_pk_mul_f32 v[30:31], v[30:31], v[32:33]
	v_bfe_u32 v1, v23, 16, 1
	v_bfe_u32 v24, v22, 16, 1
	v_bfe_u32 v25, v19, 16, 1
	v_bfe_u32 v26, v18, 16, 1
	v_add3_u32 v18, v18, v26, s72
	v_add3_u32 v19, v19, v25, s72
	v_add3_u32 v22, v22, v24, s72
	v_add3_u32 v1, v23, v1, s72
	v_bfe_u32 v23, v30, 16, 1
	v_bfe_u32 v24, v31, 16, 1
	v_bfe_u32 v25, v20, 16, 1
	v_bfe_u32 v26, v21, 16, 1
	v_add3_u32 v21, v21, v26, s72
	v_add3_u32 v20, v20, v25, s72
	v_add3_u32 v24, v31, v24, s72
	v_add3_u32 v23, v30, v23, s72
	v_lshrrev_b32_e32 v23, 16, v23
	v_lshrrev_b32_e32 v24, 16, v24
	v_lshrrev_b32_e32 v20, 16, v20
	v_lshrrev_b32_e32 v21, 16, v21
	v_and_or_b32 v21, v1, s46, v21
	v_and_or_b32 v20, v22, s46, v20
	v_and_or_b32 v19, v19, s46, v24
	v_and_or_b32 v18, v18, s46, v23
	global_store_dwordx4 v[76:77], v[18:21], off offset:48
	v_mov_b32_e32 v26, v58
	v_mov_b32_e32 v27, v60
	v_pk_mul_f32 v[26:27], v[74:75], v[26:27] op_sel_hi:[0,1]
	v_mov_b32_e32 v60, v59
	s_waitcnt vmcnt(6)
	v_mov_b64_e32 v[18:19], v[144:145]
	v_mov_b64_e32 v[20:21], v[146:147]
	v_mov_b64_e32 v[22:23], v[148:149]
	v_mov_b64_e32 v[24:25], v[150:151]
	v_mov_b32_e32 v28, v22
	v_mov_b32_e32 v29, v24
	v_pk_mul_f32 v[26:27], v[26:27], v[28:29]
	v_pk_mul_f32 v[28:29], v[74:75], v[60:61] op_sel_hi:[0,1]
	v_mov_b32_e32 v24, v23
	v_pk_mul_f32 v[22:23], v[28:29], v[24:25]
	v_mov_b32_e32 v24, v54
	v_mov_b32_e32 v25, v56
	v_pk_mul_f32 v[24:25], v[74:75], v[24:25] op_sel_hi:[0,1]
	v_mov_b32_e32 v28, v18
	v_mov_b32_e32 v29, v20
	v_mov_b32_e32 v56, v55
	v_pk_mul_f32 v[24:25], v[24:25], v[28:29]
	v_pk_mul_f32 v[28:29], v[74:75], v[56:57] op_sel_hi:[0,1]
	v_mov_b32_e32 v20, v19
	v_pk_mul_f32 v[18:19], v[28:29], v[20:21]
	v_bfe_u32 v21, v23, 16, 1
	v_bfe_u32 v1, v19, 16, 1
	v_bfe_u32 v20, v18, 16, 1
	v_bfe_u32 v28, v22, 16, 1
	v_add3_u32 v22, v22, v28, s72
	v_add3_u32 v23, v23, v21, s72
	v_add3_u32 v18, v18, v20, s72
	v_add3_u32 v1, v19, v1, s72
	v_bfe_u32 v19, v26, 16, 1
	v_bfe_u32 v20, v27, 16, 1
	v_bfe_u32 v21, v24, 16, 1
	v_bfe_u32 v28, v25, 16, 1
	v_add3_u32 v25, v25, v28, s72
	v_add3_u32 v21, v24, v21, s72
	v_add3_u32 v20, v27, v20, s72
	v_add3_u32 v19, v26, v19, s72
	v_lshrrev_b32_e32 v24, 16, v19
	v_lshrrev_b32_e32 v19, 16, v20
	v_lshrrev_b32_e32 v20, 16, v21
	v_lshrrev_b32_e32 v21, 16, v25
	v_and_or_b32 v21, v1, s46, v21
	v_and_or_b32 v20, v18, s46, v20
	v_and_or_b32 v19, v23, s46, v19
	v_and_or_b32 v18, v22, s46, v24
	global_store_dwordx4 v[76:77], v[18:21], off offset:64
	v_mov_b32_e32 v26, v50
	v_mov_b32_e32 v27, v52
	v_pk_mul_f32 v[26:27], v[74:75], v[26:27] op_sel_hi:[0,1]
	v_mov_b32_e32 v52, v51
	s_waitcnt vmcnt(4)
; __device__ __forceinline__ unsigned pk2(float lo, float hi) { return f2bf(lo) | (f2bf(hi) << 16); }
; __global__ void __launch_bounds__(NWAVES * 64, 2) fwd_kernel(Args args) {
;     ...
;                     for (int j = 0; j < 8; ++j) { const f32x4 a = av[2 * j], c2 = av[2 * j + 1], g0 = sg[2 * j], g1 = sg[2 * j + 1];
;                         v4u w; w.x = pk2(a.x * rs * g0.x, a.y * rs * g0.y); w.y = pk2(a.z * rs * g0.z, a.w * rs * g0.w); w.z = pk2(c2.x * rs * g1.x, c2.y * rs * g1.y); w.w = pk2(c2.z * rs * g1.z, c2.w * rs * g1.w);
;                         *(v4u*)(orow + 8 * j) = w; }
;                 }
;                 __syncthreads();
	v_mov_b64_e32 v[18:19], v[152:153]
	v_mov_b64_e32 v[20:21], v[154:155]
	v_mov_b64_e32 v[22:23], v[156:157]
	v_mov_b64_e32 v[24:25], v[158:159]
	v_mov_b32_e32 v28, v22
	v_mov_b32_e32 v29, v24
	v_pk_mul_f32 v[26:27], v[26:27], v[28:29]
	v_pk_mul_f32 v[28:29], v[74:75], v[52:53] op_sel_hi:[0,1]
	v_mov_b32_e32 v24, v23
	v_pk_mul_f32 v[22:23], v[28:29], v[24:25]
	v_mov_b32_e32 v24, v46
	v_mov_b32_e32 v25, v48
	v_pk_mul_f32 v[24:25], v[74:75], v[24:25] op_sel_hi:[0,1]
	v_mov_b32_e32 v28, v18
	v_mov_b32_e32 v29, v20
	v_mov_b32_e32 v48, v47
	v_pk_mul_f32 v[24:25], v[24:25], v[28:29]
	v_pk_mul_f32 v[28:29], v[74:75], v[48:49] op_sel_hi:[0,1]
	v_mov_b32_e32 v20, v19
	v_pk_mul_f32 v[18:19], v[28:29], v[20:21]
	v_bfe_u32 v21, v23, 16, 1
	v_bfe_u32 v1, v19, 16, 1
	v_bfe_u32 v20, v18, 16, 1
	v_bfe_u32 v28, v22, 16, 1
	v_add3_u32 v22, v22, v28, s72
	v_add3_u32 v23, v23, v21, s72
	v_add3_u32 v18, v18, v20, s72
	v_add3_u32 v1, v19, v1, s72
	v_bfe_u32 v19, v26, 16, 1
	v_bfe_u32 v20, v27, 16, 1
	v_bfe_u32 v21, v24, 16, 1
	v_bfe_u32 v28, v25, 16, 1
	v_add3_u32 v25, v25, v28, s72
	v_add3_u32 v21, v24, v21, s72
	v_add3_u32 v20, v27, v20, s72
	v_add3_u32 v19, v26, v19, s72
	v_lshrrev_b32_e32 v24, 16, v19
	v_lshrrev_b32_e32 v19, 16, v20
	v_lshrrev_b32_e32 v20, 16, v21
	v_lshrrev_b32_e32 v21, 16, v25
	v_and_or_b32 v21, v1, s46, v21
	v_and_or_b32 v20, v18, s46, v20
	v_and_or_b32 v19, v23, s46, v19
	v_and_or_b32 v18, v22, s46, v24
	global_store_dwordx4 v[76:77], v[18:21], off offset:80
	v_mov_b32_e32 v27, v12
	v_mov_b32_e32 v12, v11
	v_mov_b32_e32 v26, v10
	v_pk_mul_f32 v[10:11], v[74:75], v[12:13] op_sel_hi:[0,1]
	v_mov_b32_e32 v13, v16
	v_mov_b32_e32 v16, v15
	v_mov_b32_e32 v12, v14
	v_pk_mul_f32 v[14:15], v[74:75], v[16:17] op_sel_hi:[0,1]
	v_pk_mul_f32 v[26:27], v[74:75], v[26:27] op_sel_hi:[0,1]
	v_pk_mul_f32 v[12:13], v[74:75], v[12:13] op_sel_hi:[0,1]
	s_waitcnt vmcnt(2)
	v_mov_b64_e32 v[18:19], v[160:161]
	v_mov_b64_e32 v[20:21], v[162:163]
	v_mov_b64_e32 v[22:23], v[164:165]
	v_mov_b64_e32 v[24:25], v[166:167]
	v_mov_b32_e32 v29, v24
	v_mov_b32_e32 v24, v23
	v_mov_b32_e32 v23, v20
	v_mov_b32_e32 v20, v19
	v_mov_b32_e32 v28, v22
	v_pk_mul_f32 v[10:11], v[10:11], v[24:25]
	v_mov_b32_e32 v22, v18
	v_pk_mul_f32 v[14:15], v[14:15], v[20:21]
	v_pk_mul_f32 v[26:27], v[26:27], v[28:29]
	v_pk_mul_f32 v[12:13], v[12:13], v[22:23]
	v_bfe_u32 v1, v15, 16, 1
	v_bfe_u32 v16, v14, 16, 1
	v_bfe_u32 v17, v11, 16, 1
	v_bfe_u32 v18, v10, 16, 1
	v_add3_u32 v10, v10, v18, s72
	v_add3_u32 v11, v11, v17, s72
	v_add3_u32 v14, v14, v16, s72
	v_add3_u32 v1, v15, v1, s72
	v_bfe_u32 v15, v26, 16, 1
	v_bfe_u32 v16, v27, 16, 1
	v_bfe_u32 v17, v12, 16, 1
	v_bfe_u32 v18, v13, 16, 1
	v_add3_u32 v13, v13, v18, s72
	v_add3_u32 v12, v12, v17, s72
	v_add3_u32 v16, v27, v16, s72
	v_add3_u32 v15, v26, v15, s72
	v_lshrrev_b32_e32 v15, 16, v15
	v_lshrrev_b32_e32 v16, 16, v16
	v_lshrrev_b32_e32 v12, 16, v12
	v_lshrrev_b32_e32 v13, 16, v13
	v_and_or_b32 v13, v1, s46, v13
	v_and_or_b32 v12, v14, s46, v12
	v_and_or_b32 v11, v11, s46, v16
	v_and_or_b32 v10, v10, s46, v15
	global_store_dwordx4 v[76:77], v[10:13], off offset:96
	v_mov_b32_e32 v19, v8
	v_mov_b32_e32 v8, v7
	v_mov_b32_e32 v18, v6
	v_pk_mul_f32 v[6:7], v[74:75], v[8:9] op_sel_hi:[0,1]
	v_mov_b32_e32 v9, v4
	v_mov_b32_e32 v4, v3
	v_mov_b32_e32 v8, v2
	v_pk_mul_f32 v[2:3], v[74:75], v[4:5] op_sel_hi:[0,1]
	v_pk_mul_f32 v[18:19], v[74:75], v[18:19] op_sel_hi:[0,1]
	v_pk_mul_f32 v[8:9], v[74:75], v[8:9] op_sel_hi:[0,1]
	s_cselect_b64 s[4:5], -1, 0
	s_waitcnt vmcnt(0)
	v_mov_b64_e32 v[10:11], v[168:169]
	v_mov_b64_e32 v[12:13], v[170:171]
	v_mov_b64_e32 v[14:15], v[172:173]
	v_mov_b64_e32 v[16:17], v[174:175]
	v_mov_b32_e32 v21, v16
	v_mov_b32_e32 v16, v15
	v_mov_b32_e32 v15, v12
	v_mov_b32_e32 v12, v11
	v_mov_b32_e32 v20, v14
	v_pk_mul_f32 v[6:7], v[6:7], v[16:17]
	v_mov_b32_e32 v14, v10
	v_pk_mul_f32 v[2:3], v[2:3], v[12:13]
	v_pk_mul_f32 v[18:19], v[18:19], v[20:21]
	v_pk_mul_f32 v[8:9], v[8:9], v[14:15]
	v_bfe_u32 v1, v3, 16, 1
	v_bfe_u32 v4, v2, 16, 1
	v_bfe_u32 v5, v7, 16, 1
	v_bfe_u32 v10, v6, 16, 1
	v_add3_u32 v6, v6, v10, s72
	v_add3_u32 v7, v7, v5, s72
	v_add3_u32 v2, v2, v4, s72
	v_add3_u32 v1, v3, v1, s72
	v_bfe_u32 v3, v18, 16, 1
	v_bfe_u32 v4, v19, 16, 1
	v_bfe_u32 v5, v8, 16, 1
	v_bfe_u32 v10, v9, 16, 1
	v_add3_u32 v9, v9, v10, s72
	v_add3_u32 v5, v8, v5, s72
	v_add3_u32 v4, v19, v4, s72
	v_add3_u32 v3, v18, v3, s72
	v_lshrrev_b32_e32 v8, 16, v3
	v_lshrrev_b32_e32 v3, 16, v4
	v_lshrrev_b32_e32 v4, 16, v5
	v_lshrrev_b32_e32 v5, 16, v9
	v_and_or_b32 v5, v1, s46, v5
	v_and_or_b32 v4, v2, s46, v4
	v_and_or_b32 v3, v7, s46, v3
	v_and_or_b32 v2, v6, s46, v8
	global_store_dwordx4 v[76:77], v[2:5], off offset:112
	s_barrier
	s_and_b64 vcc, exec, s[4:5]
	s_cbranch_vccz .LBB0_546
	s_branch .LBB0_595
